# FFN-down: residual tile lines touched during the K loop (LDS-DMA dword per 128B line, 4 per tile) so the epilogue x loads hit cache
# baseline (speedup 1.0000x reference)
.LBB0_1246:
	s_add_u32 s41, s16, 0x100
	v_mov_b32_e32 v2, 0
	s_addc_u32 s42, s17, 0
	s_mov_b32 s43, -2
	v_mov_b32_e32 v3, v2
	v_mov_b32_e32 v4, v2
	v_mov_b32_e32 v5, v2
	v_mov_b32_e32 v6, v2
	v_mov_b32_e32 v7, v2
	v_mov_b32_e32 v8, v2
	v_mov_b32_e32 v9, v2
	v_mov_b32_e32 v10, v2
	v_mov_b32_e32 v11, v2
	v_mov_b32_e32 v12, v2
	v_mov_b32_e32 v13, v2
	v_mov_b32_e32 v14, v2
	v_mov_b32_e32 v15, v2
	v_mov_b32_e32 v16, v2
	v_mov_b32_e32 v17, v2
	v_mov_b32_e32 v34, v2
	v_mov_b32_e32 v35, v2
	v_mov_b32_e32 v36, v2
	v_mov_b32_e32 v37, v2
	v_mov_b32_e32 v38, v2
	v_mov_b32_e32 v39, v2
	v_mov_b32_e32 v40, v2
	v_mov_b32_e32 v41, v2
	v_mov_b32_e32 v46, v2
	v_mov_b32_e32 v47, v2
	v_mov_b32_e32 v48, v2
	v_mov_b32_e32 v49, v2
	v_mov_b32_e32 v50, v2
	v_mov_b32_e32 v51, v2
	v_mov_b32_e32 v52, v2
	v_mov_b32_e32 v53, v2
	v_mov_b32_e32 v18, v2
	v_mov_b32_e32 v19, v2
	v_mov_b32_e32 v20, v2
	v_mov_b32_e32 v21, v2
	v_mov_b32_e32 v22, v2
	v_mov_b32_e32 v23, v2
	v_mov_b32_e32 v24, v2
	v_mov_b32_e32 v25, v2
	v_mov_b32_e32 v26, v2
	v_mov_b32_e32 v27, v2
	v_mov_b32_e32 v28, v2
	v_mov_b32_e32 v29, v2
	v_mov_b32_e32 v30, v2
	v_mov_b32_e32 v31, v2
	v_mov_b32_e32 v32, v2
	v_mov_b32_e32 v33, v2
	v_mov_b32_e32 v42, v2
	v_mov_b32_e32 v43, v2
	v_mov_b32_e32 v44, v2
	v_mov_b32_e32 v45, v2
	v_mov_b32_e32 v54, v2
	v_mov_b32_e32 v55, v2
	v_mov_b32_e32 v56, v2
	v_mov_b32_e32 v57, v2
	v_mov_b32_e32 v58, v2
	v_mov_b32_e32 v59, v2
	v_mov_b32_e32 v60, v2
	v_mov_b32_e32 v61, v2
	v_mov_b32_e32 v62, v2
	v_mov_b32_e32 v63, v2
	v_mov_b32_e32 v64, v2
	v_mov_b32_e32 v65, v2
	v_mov_b32_e32 v66, v2
	v_mov_b32_e32 v67, v2
	v_mov_b32_e32 v68, v2
	v_mov_b32_e32 v69, v2
	v_mov_b32_e32 v70, v2
	v_mov_b32_e32 v71, v2
	v_mov_b32_e32 v72, v2
	v_mov_b32_e32 v73, v2
	v_mov_b32_e32 v78, v2
	v_mov_b32_e32 v79, v2
	v_mov_b32_e32 v80, v2
	v_mov_b32_e32 v81, v2
	v_mov_b32_e32 v82, v2
	v_mov_b32_e32 v83, v2
	v_mov_b32_e32 v84, v2
	v_mov_b32_e32 v85, v2
	v_mov_b32_e32 v114, v2
	v_mov_b32_e32 v115, v2
	v_mov_b32_e32 v116, v2
	v_mov_b32_e32 v117, v2
	v_mov_b32_e32 v118, v2
	v_mov_b32_e32 v119, v2
	v_mov_b32_e32 v120, v2
	v_mov_b32_e32 v121, v2
	v_mov_b32_e32 v126, v2
	v_mov_b32_e32 v127, v2
	v_mov_b32_e32 v128, v2
	v_mov_b32_e32 v129, v2
	v_mov_b32_e32 v130, v2
	v_mov_b32_e32 v131, v2
	v_mov_b32_e32 v132, v2
	v_mov_b32_e32 v133, v2
	v_mov_b32_e32 v74, v2
	v_mov_b32_e32 v75, v2
	v_mov_b32_e32 v76, v2
	v_mov_b32_e32 v77, v2
	v_mov_b32_e32 v86, v2
	v_mov_b32_e32 v87, v2
	v_mov_b32_e32 v88, v2
	v_mov_b32_e32 v89, v2
	v_mov_b32_e32 v90, v2
	v_mov_b32_e32 v91, v2
	v_mov_b32_e32 v92, v2
	v_mov_b32_e32 v93, v2
	v_mov_b32_e32 v94, v2
	v_mov_b32_e32 v95, v2
	v_mov_b32_e32 v96, v2
	v_mov_b32_e32 v97, v2
	v_mov_b32_e32 v122, v2
	v_mov_b32_e32 v123, v2
	v_mov_b32_e32 v124, v2
	v_mov_b32_e32 v125, v2
	v_mov_b32_e32 v134, v2
	v_mov_b32_e32 v135, v2
	v_mov_b32_e32 v136, v2
	v_mov_b32_e32 v137, v2
	v_mov_b32_e32 v138, v2
	v_mov_b32_e32 v139, v2
	v_mov_b32_e32 v140, v2
	v_mov_b32_e32 v141, v2
	v_mov_b32_e32 v142, v2
	v_mov_b32_e32 v143, v2
	v_mov_b32_e32 v144, v2
	v_mov_b32_e32 v145, v2
	v_readlane_b32 s99, v255, 41
	s_cmp_eq_u32 s36, 2
	s_cselect_b32 s99, s99, 0
	s_lshl_b32 s20, s39, 20
	s_add_u32 s18, s10, s20
	s_addc_u32 s19, s11, 0
	s_lshl_b32 s20, s40, 10
	s_add_u32 s18, s18, s20
	s_addc_u32 s19, s19, 0
	v_readfirstlane_b32 s20, v163
	v_readlane_b32 s21, v254, 0
	s_and_b32 s21, s21, s99
	s_lshl_b32 s21, s21, 19
	s_add_u32 s18, s18, s21
	s_addc_u32 s19, s19, 0
	s_lshl_b32 s21, s20, 12
	s_sub_u32 s18, s18, s21
	s_subb_u32 s19, s19, 0
	s_lshl_b32 s21, s20, 1
	s_add_u32 s18, s18, s21
	s_addc_u32 s19, s19, 0
	v_writelane_b32 v255, s18, 43
	v_writelane_b32 v255, s19, 44
	s_cmp_lg_u32 s99, 0
	s_cselect_b32 s20, 8, 24
	v_writelane_b32 v255, s20, 45

.Lfd_skip7:
	s_setprio 0
	s_barrier
	s_add_u32 s14, s18, 0xb0080
	s_addc_u32 s15, s19, 0
	s_add_i32 s18, s20, s23
	v_lshl_add_u64 v[98:99], s[14:15], 0, v[0:1]
	s_mov_b32 m0, s18
	s_nop 0
	global_load_lds_dwordx4 v[98:99], off
	v_lshl_add_u64 v[98:99], s[14:15], 0, v[146:147]
	s_add_i32 m0, s18, 0x2000
	s_nop 0
	global_load_lds_dwordx4 v[98:99], off
	s_waitcnt vmcnt(6)
	s_sub_i32 s14, s43, 0
	s_and_b32 s14, s14, 7
	s_cmp_lg_u32 s14, 0
	s_cbranch_scc1 .Lxpf_ffn_down
	s_cmp_lt_i32 s43, 0
	s_cbranch_scc1 .Lxpf_ffn_down
	v_readlane_b32 s14, v255, 45
	s_cmp_gt_i32 s43, s14
	s_cbranch_scc1 .Lxpf_ffn_down
	v_readlane_b32 s14, v255, 43
	v_readlane_b32 s15, v255, 44
	s_lshl_b32 s18, s43, 15
	s_add_u32 s14, s14, s18
	s_addc_u32 s15, s15, 0
	v_lshlrev_b32_e32 v98, 12, v163
	s_mov_b32 m0, 0x20000
	s_nop 0
	global_load_lds_dword v98, s[14:15]
.Lxpf_ffn_down:
	s_barrier
	s_setprio 1
	s_cmp_lg_u32 s99, 0
	s_cbranch_scc1 .Lfd_skip8
	v_mfma_f32_16x16x32_bf16 v[50:53], v[230:233], v[152:155], v[50:53]
	v_mfma_f32_16x16x32_bf16 v[46:49], v[238:241], v[152:155], v[46:49]
	v_mfma_f32_16x16x32_bf16 v[38:41], v[230:233], v[176:179], v[38:41]
	v_mfma_f32_16x16x32_bf16 v[34:37], v[238:241], v[176:179], v[34:37]
	v_mfma_f32_16x16x32_bf16 v[14:17], v[230:233], v[184:187], v[14:17]
	v_mfma_f32_16x16x32_bf16 v[10:13], v[238:241], v[184:187], v[10:13]
	v_mfma_f32_16x16x32_bf16 v[6:9], v[230:233], v[192:195], v[6:9]
	v_mfma_f32_16x16x32_bf16 v[2:5], v[238:241], v[192:195], v[2:5]
	v_mfma_f32_16x16x32_bf16 v[50:53], v[234:237], v[156:159], v[50:53]
	v_mfma_f32_16x16x32_bf16 v[46:49], v[242:245], v[156:159], v[46:49]
	v_mfma_f32_16x16x32_bf16 v[38:41], v[234:237], v[180:183], v[38:41]
	v_mfma_f32_16x16x32_bf16 v[34:37], v[242:245], v[180:183], v[34:37]
	v_mfma_f32_16x16x32_bf16 v[14:17], v[234:237], v[188:191], v[14:17]
	v_mfma_f32_16x16x32_bf16 v[10:13], v[242:245], v[188:191], v[10:13]
	v_mfma_f32_16x16x32_bf16 v[6:9], v[234:237], v[196:199], v[6:9]
	v_mfma_f32_16x16x32_bf16 v[2:5], v[242:245], v[196:199], v[2:5]
